# peeled last diff tile uses the hand body; select prologue loads de-serialized; gdn scan: next-chunk operand wait moved to the loop bottom
# speedup vs baseline: 1.0382x; 1.0010x over previous
; #define LAS __attribute__((address_space(3)))
; __device__ __forceinline__ void dsa_select_item(CParams& p, LAS unsigned char* lds, int b, int qblk, int tid_in, int wave) {
;     ...
;         LAS h16* Aq = (LAS h16*)(lds + 40960);
;         LAS float* Wq = (LAS float*)(lds + 77824);
;         __syncthreads();
;         {   const int Rr = tid >> 1, half = tid & 1, a = Rr >> 5, r = Rr & 31;
;             const int rho = (r & 3) + 4 * (r >> 3), hd = rho & 7, qloc = 2 * ((r >> 2) & 1) + (rho >> 3);
;             const h16* src = proj + (size_t)(tb0 + qblk * 32 + 4 * a + qloc) * OD_N + 2304 + hd * 64 + half * 32;
; #pragma unroll
;             for (int c = 0; c < 4; ++c) *(LAS h16x8*)(Aq + Rr * 72 + half * 32 + c * 8) = *(const h16x8*)(src + c * 8);
;             if (tid < 256) Wq[tid] = (float)proj[(size_t)(tb0 + qblk * 32 + (tid >> 3)) * OD_N + 2880 + (tid & 7)];
;         }
.LBB0_400:
	s_lshl_b32 s4, s82, 2
	s_and_b32 s4, s4, 8
	s_or_b32 s4, s4, s76
	s_bitcmp0_b32 s82, 0
	s_cselect_b32 s83, s73, s77
	v_mov_b32_e32 v2, v161
	s_lshl_b32 s58, s4, 12
	s_lshl_b32 s84, s83, 6
	v_ashrrev_i32_e32 v3, 1, v2
	s_waitcnt vmcnt(0)
	v_ashrrev_i32_e32 v6, 4, v2
	v_and_b32_e32 v0, 3, v3
	v_lshrrev_b32_e32 v4, 1, v3
	s_add_i32 s12, s84, s58
	v_and_b32_e32 v6, -4, v6
	v_and_or_b32 v0, v4, 4, v0
	v_and_b32_e32 v4, 2, v4
	v_bfe_u32 v5, v3, 4, 1
	v_add_u32_e32 v6, s12, v6
	v_or3_b32 v6, v4, v5, v6
	v_mov_b64_e32 v[4:5], s[14:15]
	v_mad_i64_i32 v[4:5], s[4:5], v6, s33, v[4:5]
	v_lshlrev_b32_e32 v0, 7, v0
	v_lshl_add_u64 v[4:5], v[4:5], 0, v[0:1]
	v_lshlrev_b32_e32 v0, 6, v2
	v_and_b32_e32 v0, 64, v0
	v_lshl_add_u64 v[4:5], v[4:5], 0, v[0:1]
	s_mov_b64 s[4:5], 0x1200
	v_lshl_add_u64 v[8:9], v[4:5], 0, s[4:5]
	v_add_co_u32_e32 v4, vcc, 0x1000, v4
	s_nop 1
	v_addc_co_u32_e32 v5, vcc, 0, v5, vcc
	s_barrier
	global_load_dwordx4 v[4:7], v[4:5], off offset:512
	global_load_dwordx4 v[10:13], v[8:9], off offset:16
	global_load_dwordx4 v[14:17], v[8:9], off offset:32
	global_load_dwordx4 v[18:21], v[8:9], off offset:48
	v_mul_lo_u32 v3, v3, s60
	v_add3_u32 v0, 0, v3, v0
	s_movk_i32 s4, 0x100
	v_cmp_gt_i32_e32 vcc, s4, v2
	s_waitcnt vmcnt(3)
	ds_write_b128 v0, v[4:7] offset:40960
	s_waitcnt vmcnt(2)
	ds_write_b128 v0, v[10:13] offset:40976
	s_waitcnt vmcnt(1)
	ds_write_b128 v0, v[14:17] offset:40992
	s_waitcnt vmcnt(0)
	ds_write_b128 v0, v[18:21] offset:41008
	s_and_saveexec_b64 s[4:5], vcc
	s_cbranch_execz .LBB0_402
	v_ashrrev_i32_e32 v0, 3, v2
	v_add_u32_e32 v0, s12, v0
	v_and_b32_e32 v3, 7, v2
	v_mov_b64_e32 v[4:5], s[14:15]
	v_mad_i64_i32 v[4:5], s[12:13], v0, s33, v[4:5]
	v_lshlrev_b32_e32 v0, 1, v3
	v_lshl_add_u64 v[4:5], v[4:5], 0, v[0:1]
	v_add_co_u32_e32 v4, vcc, 0x1000, v4
	v_lshl_add_u32 v3, v2, 2, 0
	s_nop 0
	v_addc_co_u32_e32 v5, vcc, 0, v5, vcc
	global_load_ushort v0, v[4:5], off offset:1664
	v_add_u32_e32 v3, 0x13000, v3
	s_waitcnt vmcnt(0)
	v_cvt_f32_f16_e32 v0, v0
	ds_write_b32 v3, v0

; #define LAS __attribute__((address_space(3)))
; __device__ __forceinline__ void dsa_select_item(CParams& p, LAS unsigned char* lds, int b, int qblk, int tid_in, int wave) {
;     ...
;         LAS h16* Aq = (LAS h16*)(lds + 40960);
;         LAS float* Wq = (LAS float*)(lds + 77824);
;         __syncthreads();
;         {   const int Rr = tid >> 1, half = tid & 1, a = Rr >> 5, r = Rr & 31;
;             const int rho = (r & 3) + 4 * (r >> 3), hd = rho & 7, qloc = 2 * ((r >> 2) & 1) + (rho >> 3);
;             const h16* src = proj + (size_t)(tb0 + qblk * 32 + 4 * a + qloc) * OD_N + 2304 + hd * 64 + half * 32;
; #pragma unroll
;             for (int c = 0; c < 4; ++c) *(LAS h16x8*)(Aq + Rr * 72 + half * 32 + c * 8) = *(const h16x8*)(src + c * 8);
;             if (tid < 256) Wq[tid] = (float)proj[(size_t)(tb0 + qblk * 32 + (tid >> 3)) * OD_N + 2880 + (tid & 7)];
;         }
.Lsel2_ret0:
.LBB0_451:
	s_or_b32 s31, s85, 1
	v_mov_b32_e32 v2, v161
	s_lshl_b32 s30, s31, 5
	v_ashrrev_i32_e32 v3, 1, v2
	v_ashrrev_i32_e32 v6, 4, v2
	v_and_b32_e32 v0, 3, v3
	v_lshrrev_b32_e32 v4, 1, v3
	s_add_i32 s12, s30, s58
	v_and_b32_e32 v6, -4, v6
	v_and_or_b32 v0, v4, 4, v0
	v_and_b32_e32 v4, 2, v4
	v_bfe_u32 v5, v3, 4, 1
	v_add_u32_e32 v6, s12, v6
	v_or3_b32 v6, v4, v5, v6
	v_mov_b64_e32 v[4:5], s[14:15]
	v_mad_i64_i32 v[4:5], s[4:5], v6, s33, v[4:5]
	v_lshlrev_b32_e32 v0, 7, v0
	v_lshl_add_u64 v[4:5], v[4:5], 0, v[0:1]
	v_lshlrev_b32_e32 v0, 6, v2
	v_and_b32_e32 v0, 64, v0
	v_lshl_add_u64 v[4:5], v[4:5], 0, v[0:1]
	s_mov_b64 s[4:5], 0x1200
	v_lshl_add_u64 v[8:9], v[4:5], 0, s[4:5]
	v_add_co_u32_e32 v4, vcc, 0x1000, v4
	s_nop 1
	v_addc_co_u32_e32 v5, vcc, 0, v5, vcc
	s_barrier
	global_load_dwordx4 v[4:7], v[4:5], off offset:512
	global_load_dwordx4 v[10:13], v[8:9], off offset:16
	global_load_dwordx4 v[14:17], v[8:9], off offset:32
	global_load_dwordx4 v[18:21], v[8:9], off offset:48
	v_mul_lo_u32 v3, v3, s60
	v_add3_u32 v0, 0, v3, v0
	s_movk_i32 s4, 0x100
	v_cmp_gt_i32_e32 vcc, s4, v2
	s_waitcnt vmcnt(3)
	ds_write_b128 v0, v[4:7] offset:40960
	s_waitcnt vmcnt(2)
	ds_write_b128 v0, v[10:13] offset:40976
	s_waitcnt vmcnt(1)
	ds_write_b128 v0, v[14:17] offset:40992
	s_waitcnt vmcnt(0)
	ds_write_b128 v0, v[18:21] offset:41008
	s_and_saveexec_b64 s[4:5], vcc
	s_cbranch_execz .LBB0_453
	v_ashrrev_i32_e32 v0, 3, v2
	v_add_u32_e32 v0, s12, v0
	v_and_b32_e32 v3, 7, v2
	v_mov_b64_e32 v[4:5], s[14:15]
	v_mad_i64_i32 v[4:5], s[12:13], v0, s33, v[4:5]
	v_lshlrev_b32_e32 v0, 1, v3
	v_lshl_add_u64 v[4:5], v[4:5], 0, v[0:1]
	v_add_co_u32_e32 v4, vcc, 0x1000, v4
	v_lshl_add_u32 v3, v2, 2, 0
	s_nop 0
	v_addc_co_u32_e32 v5, vcc, 0, v5, vcc
	global_load_ushort v0, v[4:5], off offset:1664
	v_add_u32_e32 v3, 0x13000, v3
	s_waitcnt vmcnt(0)
	v_cvt_f32_f16_e32 v0, v0
	ds_write_b32 v3, v0

; #define LAS __attribute__((address_space(3)))
; __device__ __forceinline__ f32x16 mma32(const h16x8 a, const h16x8 b, const f32x16 c) { return __builtin_amdgcn_mfma_f32_32x32x16_f16(a, b, c, 0, 0, 0); }
; __device__ __forceinline__ void diff_attn_item(CParams& p, int j, int layer, LAS unsigned char* lds, int b, int h, int qb, int tid_in, int lane_in, int wave) {
;     ...
;         if (!(k0 > q0 + 31)) {
;         f32x16 sc[2];
; #pragma unroll
;         for (int sub = 0; sub < 2; ++sub) {
; #pragma unroll
;             for (int i = 0; i < 16; ++i) sc[sub][i] = 0.f;
; #pragma unroll
;             for (int s = 0; s < 4; ++s) sc[sub] = mma32(*(const LAS h16x8*)(Ks + (32 * sub + r) * 136 + mp * 64 + 16 * s + 8 * hh), qf[s], sc[sub]);
;         }
;         float mx = -INFINITY;
;         if (k0 + 63 + 128 <= q0) {
;             const float bfar = bdl[128];
; #pragma unroll
;             for (int sub = 0; sub < 2; ++sub)
; #pragma unroll
;                 for (int i = 0; i < 16; ++i) { sc[sub][i] += bfar; mx = fmaxf(mx, sc[sub][i]); }
;         } else {
; #pragma unroll
;             for (int sub = 0; sub < 2; ++sub)
; #pragma unroll
;                 for (int i = 0; i < 16; ++i) { const int kp = k0 + 32 * sub + (i & 3) + 8 * (i >> 2) + 4 * hh; const int dist = qp - kp;
;                     const float v = dist < 0 ? -INFINITY : sc[sub][i] + bdl[dist < 128 ? dist : 128]; sc[sub][i] = v; mx = fmaxf(mx, v); }
.LBB0_672:
	s_lshl_b32 s30, s12, 6
	v_cmp_le_u32_e32 vcc, s30, v210
	s_and_saveexec_b64 s[4:5], vcc
	s_cbranch_execz .LBB0_744
	s_and_b32 s41, s12, 1
	s_waitcnt vmcnt(0)
	s_mul_i32 s6, s41, 0x4400
	v_add_u32_e32 v214, s6, v211
	ds_read_b128 v[66:69], v214 offset:0
	ds_read_b128 v[70:73], v214 offset:32
	ds_read_b128 v[74:77], v214 offset:64
	ds_read_b128 v[78:81], v214 offset:96
	ds_read_b128 v[82:85], v214 offset:8704
	ds_read_b128 v[86:89], v214 offset:8736
	ds_read_b128 v[90:93], v214 offset:8768
	ds_read_b128 v[94:97], v214 offset:8800
	s_mulk_i32 s41, 0x4800
	v_add_u32_e32 v215, s41, v195
	v_lshl_add_u32 v227, v194, 1, v215
	v_add_u32_e32 v215, v215, v196
	v_readfirstlane_b32 s6, v199
	s_mov_b32 s7, 0x11800
	s_waitcnt lgkmcnt(4)
	v_mfma_f32_32x32x16_f16 v[162:177], v[66:69], v[110:113], 0
	v_mfma_f32_32x32x16_f16 v[162:177], v[70:73], v[106:109], v[162:177]
	v_mfma_f32_32x32x16_f16 v[162:177], v[74:77], v[102:105], v[162:177]
	v_mfma_f32_32x32x16_f16 v[162:177], v[78:81], v[98:101], v[162:177]
	s_waitcnt lgkmcnt(0)
	v_mfma_f32_32x32x16_f16 v[228:243], v[82:85], v[110:113], 0
	v_mfma_f32_32x32x16_f16 v[228:243], v[86:89], v[106:109], v[228:243]
	v_mfma_f32_32x32x16_f16 v[228:243], v[90:93], v[102:105], v[228:243]
	v_mfma_f32_32x32x16_f16 v[228:243], v[94:97], v[98:101], v[228:243]
	s_sub_u32 s6, s6, s40
	s_add_u32 s6, s6, 0xbf
	s_cmp_ge_i32 s6, 0xbf
	s_cbranch_scc1 .LdiffB_far
	s_andn2_b32 s12, s6, 32
	s_cmp_eq_u32 s12, 64
	s_cbranch_scc1 .LdiffB_mid
	s_movk_i32 s12, 0x80
	v_add_u32_e32 v66, 59, v212
	v_med3_i32 v66, v66, 0, s12
	v_lshl_add_u32 v66, v66, 2, s7
	ds_read_b32 v66, v66
	v_add_u32_e32 v67, 58, v212
	v_med3_i32 v67, v67, 0, s12
	v_lshl_add_u32 v67, v67, 2, s7
	ds_read_b32 v67, v67
	v_add_u32_e32 v68, 57, v212
	v_med3_i32 v68, v68, 0, s12
	v_lshl_add_u32 v68, v68, 2, s7
	ds_read_b32 v68, v68
	v_add_u32_e32 v69, 56, v212
	v_med3_i32 v69, v69, 0, s12
	v_lshl_add_u32 v69, v69, 2, s7
	ds_read_b32 v69, v69
	v_add_u32_e32 v70, 51, v212
	v_med3_i32 v70, v70, 0, s12
	v_lshl_add_u32 v70, v70, 2, s7
	ds_read_b32 v70, v70
	v_add_u32_e32 v71, 50, v212
	v_med3_i32 v71, v71, 0, s12
	v_lshl_add_u32 v71, v71, 2, s7
	ds_read_b32 v71, v71
	v_add_u32_e32 v72, 49, v212
	v_med3_i32 v72, v72, 0, s12
	v_lshl_add_u32 v72, v72, 2, s7
	ds_read_b32 v72, v72
	v_add_u32_e32 v73, 48, v212
	v_med3_i32 v73, v73, 0, s12
	v_lshl_add_u32 v73, v73, 2, s7
	ds_read_b32 v73, v73
	v_add_u32_e32 v74, 43, v212
	v_med3_i32 v74, v74, 0, s12
	v_lshl_add_u32 v74, v74, 2, s7
	ds_read_b32 v74, v74
	v_add_u32_e32 v75, 42, v212
	v_med3_i32 v75, v75, 0, s12
	v_lshl_add_u32 v75, v75, 2, s7
	ds_read_b32 v75, v75
	v_add_u32_e32 v76, 41, v212
	v_med3_i32 v76, v76, 0, s12
	v_lshl_add_u32 v76, v76, 2, s7
	ds_read_b32 v76, v76
	v_add_u32_e32 v77, 40, v212
	v_med3_i32 v77, v77, 0, s12
	v_lshl_add_u32 v77, v77, 2, s7
	ds_read_b32 v77, v77
	v_add_u32_e32 v78, 35, v212
	v_med3_i32 v78, v78, 0, s12
	v_lshl_add_u32 v78, v78, 2, s7
	ds_read_b32 v78, v78
	v_add_u32_e32 v79, 34, v212
	v_med3_i32 v79, v79, 0, s12
	v_lshl_add_u32 v79, v79, 2, s7
	ds_read_b32 v79, v79
	v_add_u32_e32 v80, 33, v212
	v_med3_i32 v80, v80, 0, s12
	v_lshl_add_u32 v80, v80, 2, s7
	ds_read_b32 v80, v80
	v_add_u32_e32 v81, 32, v212
	v_med3_i32 v81, v81, 0, s12
	v_lshl_add_u32 v81, v81, 2, s7
	ds_read_b32 v81, v81
	v_add_u32_e32 v82, 27, v212
	v_med3_i32 v82, v82, 0, s12
	v_lshl_add_u32 v82, v82, 2, s7
	ds_read_b32 v82, v82
	v_add_u32_e32 v83, 26, v212
	v_med3_i32 v83, v83, 0, s12
	v_lshl_add_u32 v83, v83, 2, s7
	ds_read_b32 v83, v83
	v_add_u32_e32 v84, 25, v212
	v_med3_i32 v84, v84, 0, s12
	v_lshl_add_u32 v84, v84, 2, s7
	ds_read_b32 v84, v84
	v_add_u32_e32 v85, 24, v212
	v_med3_i32 v85, v85, 0, s12
	v_lshl_add_u32 v85, v85, 2, s7
	ds_read_b32 v85, v85
	v_add_u32_e32 v86, 19, v212
	v_med3_i32 v86, v86, 0, s12
	v_lshl_add_u32 v86, v86, 2, s7
	ds_read_b32 v86, v86
	v_add_u32_e32 v87, 18, v212
	v_med3_i32 v87, v87, 0, s12
	v_lshl_add_u32 v87, v87, 2, s7
	ds_read_b32 v87, v87
	v_add_u32_e32 v88, 17, v212
	v_med3_i32 v88, v88, 0, s12
	v_lshl_add_u32 v88, v88, 2, s7
	ds_read_b32 v88, v88
	v_add_u32_e32 v89, 16, v212
	v_med3_i32 v89, v89, 0, s12
	v_lshl_add_u32 v89, v89, 2, s7
	ds_read_b32 v89, v89
	v_add_u32_e32 v90, 11, v212
	v_med3_i32 v90, v90, 0, s12
	v_lshl_add_u32 v90, v90, 2, s7
	ds_read_b32 v90, v90
	v_add_u32_e32 v91, 10, v212
	v_med3_i32 v91, v91, 0, s12
	v_lshl_add_u32 v91, v91, 2, s7
	ds_read_b32 v91, v91
	v_add_u32_e32 v92, 9, v212
	v_med3_i32 v92, v92, 0, s12
	v_lshl_add_u32 v92, v92, 2, s7
	ds_read_b32 v92, v92
	v_add_u32_e32 v93, 8, v212
	v_med3_i32 v93, v93, 0, s12
	v_lshl_add_u32 v93, v93, 2, s7
	ds_read_b32 v93, v93
	v_add_u32_e32 v94, 3, v212
	v_med3_i32 v94, v94, 0, s12
	v_lshl_add_u32 v94, v94, 2, s7
	ds_read_b32 v94, v94
	v_add_u32_e32 v95, 2, v212
	v_med3_i32 v95, v95, 0, s12
	v_lshl_add_u32 v95, v95, 2, s7
	ds_read_b32 v95, v95
	v_add_u32_e32 v96, 1, v212
	v_med3_i32 v96, v96, 0, s12
	v_lshl_add_u32 v96, v96, 2, s7
	ds_read_b32 v96, v96
	v_add_u32_e32 v97, 0, v212
	v_med3_i32 v97, v97, 0, s12
	v_lshl_add_u32 v97, v97, 2, s7
	ds_read_b32 v97, v97
	v_sub_u32_e32 v145, 0, v212
	v_mov_b32_e32 v144, 0xff800000
	s_nop 4
	s_waitcnt lgkmcnt(0)
; __device__ __forceinline__ void diff_attn_item(CParams& p, int j, int layer, LAS unsigned char* lds, int b, int h, int qb, int tid_in, int lane_in, int wave) {
;     ...
; #pragma unroll
;             for (int sub = 0; sub < 2; ++sub)
; #pragma unroll
;                 for (int i = 0; i < 16; ++i) { const int kp = k0 + 32 * sub + (i & 3) + 8 * (i >> 2) + 4 * hh; const int dist = qp - kp;
;                     const float v = dist < 0 ? -INFINITY : sc[sub][i] + bdl[dist < 128 ? dist : 128]; sc[sub][i] = v; mx = fmaxf(mx, v); }
;         }
	v_pk_add_f32 v[162:163], v[162:163], v[66:67]
	v_pk_add_f32 v[164:165], v[164:165], v[68:69]
	v_pk_add_f32 v[166:167], v[166:167], v[70:71]
	v_pk_add_f32 v[168:169], v[168:169], v[72:73]
	v_pk_add_f32 v[170:171], v[170:171], v[74:75]
	v_pk_add_f32 v[172:173], v[172:173], v[76:77]
	v_pk_add_f32 v[174:175], v[174:175], v[78:79]
	v_pk_add_f32 v[176:177], v[176:177], v[80:81]
	v_pk_add_f32 v[228:229], v[228:229], v[82:83]
	v_pk_add_f32 v[230:231], v[230:231], v[84:85]
	v_pk_add_f32 v[232:233], v[232:233], v[86:87]
	v_pk_add_f32 v[234:235], v[234:235], v[88:89]
	v_pk_add_f32 v[236:237], v[236:237], v[90:91]
	v_pk_add_f32 v[238:239], v[238:239], v[92:93]
	v_pk_add_f32 v[240:241], v[240:241], v[94:95]
	v_pk_add_f32 v[242:243], v[242:243], v[96:97]
	v_cmp_ge_i32_e64 s[46:47], 59, v145
	v_cmp_ge_i32_e64 s[48:49], 58, v145
	v_cmp_ge_i32_e64 s[50:51], 57, v145
	v_cndmask_b32_e64 v162, v144, v162, s[46:47]
	v_cmp_ge_i32_e64 s[52:53], 56, v145
	v_cndmask_b32_e64 v163, v144, v163, s[48:49]
	v_cmp_ge_i32_e64 s[46:47], 51, v145
	v_cndmask_b32_e64 v164, v144, v164, s[50:51]
	v_cmp_ge_i32_e64 s[48:49], 50, v145
	v_cndmask_b32_e64 v165, v144, v165, s[52:53]
	v_cmp_ge_i32_e64 s[50:51], 49, v145
	v_cndmask_b32_e64 v166, v144, v166, s[46:47]
	v_cmp_ge_i32_e64 s[52:53], 48, v145
	v_cndmask_b32_e64 v167, v144, v167, s[48:49]
	v_cmp_ge_i32_e64 s[46:47], 43, v145
	v_cndmask_b32_e64 v168, v144, v168, s[50:51]
	v_cmp_ge_i32_e64 s[48:49], 42, v145
	v_cndmask_b32_e64 v169, v144, v169, s[52:53]
	v_cmp_ge_i32_e64 s[50:51], 41, v145
	v_cndmask_b32_e64 v170, v144, v170, s[46:47]
	v_cmp_ge_i32_e64 s[52:53], 40, v145
	v_cndmask_b32_e64 v171, v144, v171, s[48:49]
	v_cmp_ge_i32_e64 s[46:47], 35, v145
	v_cndmask_b32_e64 v172, v144, v172, s[50:51]
	v_cmp_ge_i32_e64 s[48:49], 34, v145
	v_cndmask_b32_e64 v173, v144, v173, s[52:53]
	v_cmp_ge_i32_e64 s[50:51], 33, v145
	v_cndmask_b32_e64 v174, v144, v174, s[46:47]
	v_cmp_ge_i32_e64 s[52:53], 32, v145
	v_cndmask_b32_e64 v175, v144, v175, s[48:49]
	v_cmp_ge_i32_e64 s[46:47], 27, v145
	v_cndmask_b32_e64 v176, v144, v176, s[50:51]
	v_cmp_ge_i32_e64 s[48:49], 26, v145
	v_cndmask_b32_e64 v177, v144, v177, s[52:53]
	v_cmp_ge_i32_e64 s[50:51], 25, v145
	v_cndmask_b32_e64 v228, v144, v228, s[46:47]
	v_cmp_ge_i32_e64 s[52:53], 24, v145
	v_cndmask_b32_e64 v229, v144, v229, s[48:49]
	v_cmp_ge_i32_e64 s[46:47], 19, v145
	v_cndmask_b32_e64 v230, v144, v230, s[50:51]
	v_cmp_ge_i32_e64 s[48:49], 18, v145
	v_cndmask_b32_e64 v231, v144, v231, s[52:53]
	v_cmp_ge_i32_e64 s[50:51], 17, v145
	v_cndmask_b32_e64 v232, v144, v232, s[46:47]
	v_cmp_ge_i32_e64 s[52:53], 16, v145
	v_cndmask_b32_e64 v233, v144, v233, s[48:49]
	v_cmp_ge_i32_e64 s[46:47], 11, v145
	v_cndmask_b32_e64 v234, v144, v234, s[50:51]
	v_cmp_ge_i32_e64 s[48:49], 10, v145
	v_cndmask_b32_e64 v235, v144, v235, s[52:53]
	v_cmp_ge_i32_e64 s[50:51], 9, v145
	v_cndmask_b32_e64 v236, v144, v236, s[46:47]
	v_cmp_ge_i32_e64 s[52:53], 8, v145
	v_cndmask_b32_e64 v237, v144, v237, s[48:49]
	v_cmp_ge_i32_e64 s[46:47], 3, v145
	v_cndmask_b32_e64 v238, v144, v238, s[50:51]
	v_cmp_ge_i32_e64 s[48:49], 2, v145
	v_cndmask_b32_e64 v239, v144, v239, s[52:53]
	v_cmp_ge_i32_e64 s[50:51], 1, v145
	v_cndmask_b32_e64 v240, v144, v240, s[46:47]
	v_cmp_ge_i32_e64 s[52:53], 0, v145
	v_cndmask_b32_e64 v241, v144, v241, s[48:49]
	v_cndmask_b32_e64 v242, v144, v242, s[50:51]
	v_cndmask_b32_e64 v243, v144, v243, s[52:53]
	v_mov_b32_e32 v213, 0
	s_branch .LdiffB_max

; #define LAS __attribute__((address_space(3)))
; __device__ __forceinline__ f32x16 mma32(const h16x8 a, const h16x8 b, const f32x16 c) { return __builtin_amdgcn_mfma_f32_32x32x16_f16(a, b, c, 0, 0, 0); }
; __device__ __forceinline__ void diff_attn_item(CParams& p, int j, int layer, LAS unsigned char* lds, int b, int h, int qb, int tid_in, int lane_in, int wave) {
;     ...
; #pragma unroll
;         for (int sub = 0; sub < 2; ++sub)
; #pragma unroll
;             for (int s2 = 0; s2 < 2; ++s2) {
;                 h16x8 pf;
; #pragma unroll
;                 for (int jj = 0; jj < 8; ++jj) pf[jj] = (h16)sc[sub][8 * s2 + jj];
; #pragma unroll
;                 for (int d = 0; d < 4; ++d) {
;                     const int coff = 32 * d * 72 + ((((sub << 1) | s2) ^ d) << 4);
;                     const h16x4 lo = *(const LAS h16x4*)(Vt + vlo + coff), hi = *(const LAS h16x4*)(Vt + vhi + coff);
;                     h16x8 vf; vf[0] = lo[0]; vf[1] = lo[1]; vf[2] = lo[2]; vf[3] = lo[3]; vf[4] = hi[0]; vf[5] = hi[1]; vf[6] = hi[2]; vf[7] = hi[3];
;                     o[d] = mma32(vf, pf, o[d]);
;                 }
;             }
;         }
;         __syncthreads();
;     }
;     const float inv = 1.f / l_run;
;     if (mp == 1) {
; #pragma unroll
;         for (int d = 0; d < 4; ++d)
; #pragma unroll
;             for (int i = 0; i < 16; ++i) Ox[(qs * 64 + d * 16 + i) * 64 + lane] = o[d][i] * inv;
;     }
;     __syncthreads();
.LdiffB_noresc:
	ds_read_b64 v[82:83], v215 offset:34848
	ds_read_b64 v[84:85], v227 offset:34848
	ds_read_b64 v[86:87], v215 offset:39424
	ds_read_b64 v[88:89], v227 offset:39424
	ds_read_b64 v[90:91], v215 offset:44128
	ds_read_b64 v[92:93], v227 offset:44128
	ds_read_b64 v[94:95], v215 offset:48704
	ds_read_b64 v[96:97], v227 offset:48704
	s_waitcnt lgkmcnt(8)
	v_mfma_f32_32x32x16_f16 v[50:65], v[66:69], v[144:147], v[50:65]
	v_mfma_f32_32x32x16_f16 v[34:49], v[70:73], v[144:147], v[34:49]
	v_mfma_f32_32x32x16_f16 v[18:33], v[74:77], v[144:147], v[18:33]
	v_mfma_f32_32x32x16_f16 v[2:17], v[78:81], v[144:147], v[2:17]
	ds_read_b64 v[66:67], v215 offset:34880
	ds_read_b64 v[68:69], v227 offset:34880
	ds_read_b64 v[70:71], v215 offset:39520
	ds_read_b64 v[72:73], v227 offset:39520
	ds_read_b64 v[74:75], v215 offset:44032
	ds_read_b64 v[76:77], v227 offset:44032
	ds_read_b64 v[78:79], v215 offset:48672
	ds_read_b64 v[80:81], v227 offset:48672
	s_waitcnt lgkmcnt(8)
	v_mfma_f32_32x32x16_f16 v[50:65], v[82:85], v[148:151], v[50:65]
	v_mfma_f32_32x32x16_f16 v[34:49], v[86:89], v[148:151], v[34:49]
	v_mfma_f32_32x32x16_f16 v[18:33], v[90:93], v[148:151], v[18:33]
	v_mfma_f32_32x32x16_f16 v[2:17], v[94:97], v[148:151], v[2:17]
	ds_read_b64 v[82:83], v215 offset:34912
	ds_read_b64 v[84:85], v227 offset:34912
	ds_read_b64 v[86:87], v215 offset:39488
	ds_read_b64 v[88:89], v227 offset:39488
	ds_read_b64 v[90:91], v215 offset:44064
	ds_read_b64 v[92:93], v227 offset:44064
	ds_read_b64 v[94:95], v215 offset:48640
	ds_read_b64 v[96:97], v227 offset:48640
	s_waitcnt lgkmcnt(8)
	v_mfma_f32_32x32x16_f16 v[50:65], v[66:69], v[152:155], v[50:65]
	v_mfma_f32_32x32x16_f16 v[34:49], v[70:73], v[152:155], v[34:49]
	v_mfma_f32_32x32x16_f16 v[18:33], v[74:77], v[152:155], v[18:33]
	v_mfma_f32_32x32x16_f16 v[2:17], v[78:81], v[152:155], v[2:17]
	s_waitcnt lgkmcnt(0)
	v_mfma_f32_32x32x16_f16 v[50:65], v[82:85], v[178:181], v[50:65]
	v_mfma_f32_32x32x16_f16 v[34:49], v[86:89], v[178:181], v[34:49]
	v_mfma_f32_32x32x16_f16 v[18:33], v[90:93], v[178:181], v[18:33]
	v_mfma_f32_32x32x16_f16 v[2:17], v[94:97], v[178:181], v[2:17]
.LBB0_744:
	s_or_b64 exec, exec, s[4:5]
	v_div_scale_f32 v66, s[4:5], v197, v197, 1.0
	v_rcp_f32_e32 v67, v66
	s_barrier
	v_fma_f32 v68, -v66, v67, 1.0
	v_fmac_f32_e32 v67, v68, v67
	v_div_scale_f32 v68, vcc, 1.0, v197, 1.0
	v_mul_f32_e32 v69, v68, v67
	v_fma_f32 v70, -v66, v69, v68
	v_fmac_f32_e32 v69, v70, v67
	v_fma_f32 v66, -v66, v69, v68
	v_div_fmas_f32 v66, v66, v67, v69
	v_div_fixup_f32 v68, v66, v197, 1.0
	s_and_saveexec_b64 s[4:5], s[8:9]
	s_cbranch_execz .LBB0_746
	v_mul_f32_e32 v66, v50, v68
	v_lshl_add_u32 v67, v193, 2, v188
	v_mul_f32_e32 v69, v51, v68
	ds_write2st64_b32 v67, v66, v69 offset1:1
	v_mul_f32_e32 v66, v52, v68
	v_mul_f32_e32 v69, v53, v68
	ds_write2st64_b32 v67, v66, v69 offset0:2 offset1:3
	v_mul_f32_e32 v66, v54, v68
	v_mul_f32_e32 v69, v55, v68
	ds_write2st64_b32 v67, v66, v69 offset0:4 offset1:5
	v_mul_f32_e32 v66, v56, v68
	v_mul_f32_e32 v69, v57, v68
	ds_write2st64_b32 v67, v66, v69 offset0:6 offset1:7
	v_mul_f32_e32 v66, v58, v68
	v_mul_f32_e32 v69, v59, v68
	ds_write2st64_b32 v67, v66, v69 offset0:8 offset1:9
	v_mul_f32_e32 v66, v60, v68
	v_mul_f32_e32 v69, v61, v68
	ds_write2st64_b32 v67, v66, v69 offset0:10 offset1:11
	v_mul_f32_e32 v66, v62, v68
	v_mul_f32_e32 v69, v63, v68
	ds_write2st64_b32 v67, v66, v69 offset0:12 offset1:13
	v_mul_f32_e32 v66, v64, v68
	v_mul_f32_e32 v69, v65, v68
	ds_write2st64_b32 v67, v66, v69 offset0:14 offset1:15
	v_mul_f32_e32 v66, v34, v68
	v_mul_f32_e32 v69, v35, v68
	ds_write2st64_b32 v67, v66, v69 offset0:16 offset1:17
	v_mul_f32_e32 v66, v36, v68
	v_mul_f32_e32 v69, v37, v68
	ds_write2st64_b32 v67, v66, v69 offset0:18 offset1:19
	v_mul_f32_e32 v66, v38, v68
	v_mul_f32_e32 v69, v39, v68
	ds_write2st64_b32 v67, v66, v69 offset0:20 offset1:21
	v_mul_f32_e32 v66, v40, v68
	v_mul_f32_e32 v69, v41, v68
	ds_write2st64_b32 v67, v66, v69 offset0:22 offset1:23
	v_mul_f32_e32 v66, v42, v68
	v_mul_f32_e32 v69, v43, v68
	ds_write2st64_b32 v67, v66, v69 offset0:24 offset1:25
	v_mul_f32_e32 v66, v44, v68
	v_mul_f32_e32 v69, v45, v68
	ds_write2st64_b32 v67, v66, v69 offset0:26 offset1:27
	v_mul_f32_e32 v66, v46, v68
	v_mul_f32_e32 v69, v47, v68
	ds_write2st64_b32 v67, v66, v69 offset0:28 offset1:29
	v_mul_f32_e32 v66, v48, v68
	v_mul_f32_e32 v69, v49, v68
	ds_write2st64_b32 v67, v66, v69 offset0:30 offset1:31
	v_mul_f32_e32 v66, v18, v68
	v_mul_f32_e32 v69, v19, v68
	ds_write2st64_b32 v67, v66, v69 offset0:32 offset1:33
	v_mul_f32_e32 v66, v20, v68
	v_mul_f32_e32 v69, v21, v68
	ds_write2st64_b32 v67, v66, v69 offset0:34 offset1:35
	v_mul_f32_e32 v66, v22, v68
	v_mul_f32_e32 v69, v23, v68
	ds_write2st64_b32 v67, v66, v69 offset0:36 offset1:37
	v_mul_f32_e32 v66, v24, v68
	v_mul_f32_e32 v69, v25, v68
	ds_write2st64_b32 v67, v66, v69 offset0:38 offset1:39
	v_mul_f32_e32 v66, v26, v68
	v_mul_f32_e32 v69, v27, v68
	ds_write2st64_b32 v67, v66, v69 offset0:40 offset1:41
	v_mul_f32_e32 v66, v28, v68
	v_mul_f32_e32 v69, v29, v68
	ds_write2st64_b32 v67, v66, v69 offset0:42 offset1:43
	v_mul_f32_e32 v66, v30, v68
	v_mul_f32_e32 v69, v31, v68
	ds_write2st64_b32 v67, v66, v69 offset0:44 offset1:45
	v_mul_f32_e32 v66, v32, v68
	v_mul_f32_e32 v69, v33, v68
	ds_write2st64_b32 v67, v66, v69 offset0:46 offset1:47
	v_mul_f32_e32 v66, v2, v68
	v_mul_f32_e32 v69, v3, v68
	ds_write2st64_b32 v67, v66, v69 offset0:48 offset1:49
	v_mul_f32_e32 v66, v4, v68
	v_mul_f32_e32 v69, v5, v68
	ds_write2st64_b32 v67, v66, v69 offset0:50 offset1:51
	v_mul_f32_e32 v66, v6, v68
	v_mul_f32_e32 v69, v7, v68
	ds_write2st64_b32 v67, v66, v69 offset0:52 offset1:53
	v_mul_f32_e32 v66, v8, v68
	v_mul_f32_e32 v69, v9, v68
	ds_write2st64_b32 v67, v66, v69 offset0:54 offset1:55
	v_mul_f32_e32 v66, v10, v68
	v_mul_f32_e32 v69, v11, v68
	ds_write2st64_b32 v67, v66, v69 offset0:56 offset1:57
	v_mul_f32_e32 v66, v12, v68
	v_mul_f32_e32 v69, v13, v68
	ds_write2st64_b32 v67, v66, v69 offset0:58 offset1:59
	v_mul_f32_e32 v66, v14, v68
	v_mul_f32_e32 v69, v15, v68
	ds_write2st64_b32 v67, v66, v69 offset0:60 offset1:61
	v_mul_f32_e32 v66, v16, v68
	v_mul_f32_e32 v69, v17, v68
	ds_write2st64_b32 v67, v66, v69 offset0:62 offset1:63

; #define LAS __attribute__((address_space(3)))
; __device__ __forceinline__ f32x4 mma16(const h16x8 a, const h16x8 b, const f32x4 c) { return __builtin_amdgcn_mfma_f32_16x16x32_f16(a, b, c, 0, 0, 0); }
; __device__ __forceinline__ void phase_gdn_scan(const int wid_s, CParams& p, LAS unsigned char* lds) {
;     ...
;         SCAN_LOAD(wf, uu, qf, inf, kf, egl, 0);
;         for (int n = 0; n < 64; ++n) {
;             const int tc0 = b * SEQ + n * 64;
;             const LAS h16* Sc = St + cur * (32 * 136); LAS h16* Sn = St + (cur ^ 1) * (32 * 136);
;             { const int nn = n + 1 < 64 ? n + 1 : n; SCAN_LOAD(wfn, uun, qfn, infn, kfn, egln, nn); }
;             {
;                 f32x4 acc = {0.f, 0.f, 0.f, 0.f};
; #pragma unroll
;                 for (int ks = 0; ks < 4; ++ks) acc = mma16(*(const LAS h16x8*)(Sc + (16 * vt + lr) * 136 + 32 * ks + 8 * lq), wf[ks], acc);
; #pragma unroll
;                 for (int r = 0; r < 4; ++r) Vnt[(16 * vt + 4 * lq + r) * 72 + 16 * wq + lr] = (h16)((float)uu[r] - acc[r]);
;             }
;             __syncthreads();
;             {
;                 f32x4 acc = {0.f, 0.f, 0.f, 0.f};
; #pragma unroll
;                 for (int ks = 0; ks < 4; ++ks) acc = mma16(qf[ks], *(const LAS h16x8*)(Sc + (16 * vt + lr) * 136 + 32 * ks + 8 * lq), acc);
; #pragma unroll
;                 for (int ks = 0; ks < 2; ++ks) acc = mma16(inf[ks], *(const LAS h16x8*)(Vnt + (16 * vt + lr) * 72 + 32 * ks + 8 * lq), acc);
; #pragma unroll
;                 for (int r = 0; r < 4; ++r) y[(size_t)(tc0 + 16 * wq + 4 * lq + r) * D + 512 + h * 128 + 32 * sl + 16 * vt + lr] = (h16)acc[r];
.LBB0_1284:
	s_or_b64 exec, exec, s[10:11]
	s_lshl_b32 s10, s18, 8
	s_and_b32 s10, s10, 0xfffff000
	v_add_u32_e32 v2, s10, v116
	v_mov_b64_e32 v[4:5], s[4:5]
	s_bfe_u32 s7, s18, 0x20002
	v_ashrrev_i32_e32 v3, 31, v2
	v_mad_i64_i32 v[4:5], s[12:13], v2, s86, v[4:5]
	s_ashr_i32 s11, s10, 4
	s_lshl_b32 s58, s7, 8
	s_lshl_b32 s12, s18, 6
	v_lshlrev_b64 v[2:3], 10, v[2:3]
	v_lshl_add_u64 v[4:5], v[4:5], 0, s[58:59]
	s_and_b32 s12, s12, 0xc0
	s_mov_b32 s13, s59
	v_lshl_add_u64 v[2:3], s[8:9], 0, v[2:3]
	s_or_b32 s20, s11, s7
	v_lshl_add_u64 v[10:11], v[4:5], 0, v[0:1]
	v_lshl_add_u64 v[4:5], v[4:5], 0, s[12:13]
	v_mov_b32_e32 v135, v1
	v_lshl_add_u64 v[2:3], v[2:3], 0, s[58:59]
	s_ashr_i32 s21, s20, 31
	v_lshl_add_u64 v[4:5], v[4:5], 0, v[134:135]
	v_mov_b32_e32 v137, v1
	v_lshl_add_u64 v[2:3], v[2:3], 0, v[0:1]
	s_lshl_b64 s[22:23], s[20:21], 13
	s_waitcnt lgkmcnt(0)
	s_barrier
	global_load_dwordx4 v[90:93], v[10:11], off offset:64
	global_load_dwordx4 v[98:101], v[10:11], off offset:128
	v_lshl_add_u64 v[4:5], v[4:5], 0, v[136:137]
	global_load_dwordx4 v[38:41], v[10:11], off offset:192
	global_load_dwordx2 v[140:141], v[4:5], off offset:1024
	global_load_dwordx4 v[94:97], v[2:3], off
	global_load_dwordx4 v[102:105], v[2:3], off offset:64
	global_load_dwordx4 v[106:109], v[2:3], off offset:128
	global_load_dwordx4 v[30:33], v[2:3], off offset:192
	v_lshl_add_u64 v[2:3], v[130:131], 0, s[22:23]
	s_lshl_b64 s[22:23], s[20:21], 7
	global_load_dwordx4 v[34:37], v[2:3], off
	global_load_dwordx4 v[26:29], v[2:3], off offset:64
	v_mov_b32_e32 v3, s23
	v_or_b32_e32 v2, s22, v114
	v_lshl_add_u64 v[4:5], v[2:3], 0, v[120:121]
	v_lshl_add_u64 v[2:3], v[2:3], 0, v[132:133]
	s_and_b32 s6, s17, 0xfffff000
	v_lshlrev_b64 v[4:5], 7, v[4:5]
	v_lshlrev_b64 v[2:3], 7, v[2:3]
	s_lshl_b64 s[20:21], s[20:21], 2
	v_lshl_add_u64 v[4:5], v[122:123], 0, v[4:5]
	v_lshl_add_u64 v[2:3], v[122:123], 0, v[2:3]
	s_add_u32 s20, s15, s20
	global_load_dwordx4 v[18:21], v[4:5], off
	global_load_dwordx4 v[14:17], v[4:5], off offset:64
	global_load_dwordx4 v[6:9], v[2:3], off
	s_nop 0
	global_load_dwordx4 v[2:5], v[2:3], off offset:64
	s_addc_u32 s21, s16, s21
	global_load_dwordx4 v[110:113], v[10:11], off
	global_load_dword v154, v1, s[20:21]
	v_lshl_add_u64 v[10:11], v[128:129], 0, s[58:59]
	s_add_u32 s11, s4, s58
	v_lshl_add_u64 v[10:11], v[10:11], 0, s[12:13]
	s_addc_u32 s13, s5, 0
	s_add_u32 s12, s11, s12
	s_addc_u32 s13, s13, 0
	v_lshl_add_u64 v[138:139], v[10:11], 0, v[134:135]
	v_lshl_add_u64 v[10:11], s[12:13], 0, v[134:135]
	v_lshl_add_u64 v[146:147], v[10:11], 0, v[136:137]
	v_mov_b32_e32 v10, 0
	v_add_u32_e32 v155, s6, v119
	v_add_u32_e32 v161, s6, v152
	v_lshl_add_u64 v[142:143], v[124:125], 0, s[58:59]
	v_lshl_add_u64 v[144:145], v[126:127], 0, s[58:59]
	s_mov_b32 s12, 0
	s_mov_b32 s11, 0
	v_mov_b32_e32 v11, v10
	v_mov_b32_e32 v12, v10
	v_mov_b32_e32 v13, v10
	v_mov_b32_e32 v22, v10
	v_mov_b32_e32 v23, v10
	v_mov_b32_e32 v24, v10
	v_mov_b32_e32 v25, v10
	s_waitcnt vmcnt(0)
.LBB0_1285:
	v_mov_b64_e32 v[68:69], v[4:5]
	v_mov_b64_e32 v[66:67], v[2:3]
	s_add_i32 s13, s12, 64
	v_add_u32_e32 v2, s12, v161
	v_mov_b64_e32 v[168:169], v[40:41]
	s_add_i32 s19, s13, s6
	v_mad_i64_i32 v[4:5], s[20:21], v2, s86, v[142:143]
	v_mov_b64_e32 v[166:167], v[38:39]
	s_ashr_i32 s22, s19, 4
	global_load_dwordx4 v[62:65], v[4:5], off
	global_load_dwordx4 v[58:61], v[4:5], off offset:64
	global_load_dwordx4 v[54:57], v[4:5], off offset:128
	global_load_dwordx4 v[38:41], v[4:5], off offset:192
	v_mad_i64_i32 v[4:5], s[20:21], v2, s86, v[146:147]
	v_ashrrev_i32_e32 v3, 31, v2
	s_or_b32 s20, s22, s7
	v_lshlrev_b64 v[2:3], 10, v[2:3]
	s_ashr_i32 s21, s20, 31
	v_mov_b64_e32 v[164:165], v[32:33]
	v_lshl_add_u64 v[2:3], v[144:145], 0, v[2:3]
	s_lshl_b64 s[22:23], s[20:21], 13
	v_mov_b64_e32 v[162:163], v[30:31]
	v_mov_b64_e32 v[174:175], v[140:141]
	v_mov_b64_e32 v[88:89], v[36:37]
	v_mov_b64_e32 v[84:85], v[28:29]
	global_load_dwordx2 v[140:141], v[4:5], off offset:1024
	global_load_dwordx4 v[50:53], v[2:3], off
	global_load_dwordx4 v[46:49], v[2:3], off offset:64
	global_load_dwordx4 v[42:45], v[2:3], off offset:128
	global_load_dwordx4 v[30:33], v[2:3], off offset:192
	v_lshl_add_u64 v[2:3], v[130:131], 0, s[22:23]
	s_lshl_b64 s[22:23], s[20:21], 7
	v_mov_b64_e32 v[86:87], v[34:35]
	v_mov_b64_e32 v[82:83], v[26:27]
	global_load_dwordx4 v[34:37], v[2:3], off
	global_load_dwordx4 v[26:29], v[2:3], off offset:64
	v_mov_b32_e32 v3, s23
	v_or_b32_e32 v2, s22, v114
	v_lshl_add_u64 v[4:5], v[2:3], 0, v[120:121]
	v_lshl_add_u64 v[2:3], v[2:3], 0, v[132:133]
	s_mul_i32 s24, s11, 0x2200
	v_lshlrev_b64 v[4:5], 7, v[4:5]
	v_lshlrev_b64 v[2:3], 7, v[2:3]
	v_mov_b64_e32 v[80:81], v[20:21]
	v_mov_b64_e32 v[76:77], v[16:17]
	v_mov_b64_e32 v[72:73], v[8:9]
	v_lshl_add_u64 v[4:5], v[122:123], 0, v[4:5]
	v_lshl_add_u64 v[2:3], v[122:123], 0, v[2:3]
	v_add_u32_e32 v135, s24, v117
	v_mov_b64_e32 v[78:79], v[18:19]
	v_mov_b64_e32 v[74:75], v[14:15]
	v_mov_b64_e32 v[70:71], v[6:7]
	global_load_dwordx4 v[18:21], v[4:5], off
	global_load_dwordx4 v[14:17], v[4:5], off offset:64
	global_load_dwordx4 v[6:9], v[2:3], off
	s_nop 0
	global_load_dwordx4 v[2:5], v[2:3], off offset:64
	ds_read_b128 v[170:173], v135
	s_waitcnt lgkmcnt(0)
	v_mfma_f32_16x16x32_f16 v[110:113], v[170:173], v[110:113], 0
	ds_read_b128 v[170:173], v135 offset:64
	s_xor_b32 s11, s11, 1
	s_lshl_b64 s[20:21], s[20:21], 2
	s_waitcnt lgkmcnt(0)
	v_mfma_f32_16x16x32_f16 v[90:93], v[170:173], v[90:93], v[110:113]
	s_nop 2
	ds_read_b128 v[110:113], v135 offset:128
	s_add_u32 s20, s15, s20
	s_addc_u32 s21, s16, s21
	s_waitcnt lgkmcnt(0)
	v_mfma_f32_16x16x32_f16 v[90:93], v[110:113], v[98:101], v[90:93]
	ds_read_b128 v[98:101], v135 offset:192
	s_nop 0
	v_mov_b32_e32 v137, v154
	global_load_dword v154, v1, s[20:21]
	s_waitcnt lgkmcnt(0)
	v_mfma_f32_16x16x32_f16 v[90:93], v[98:101], v[166:169], v[90:93]
	v_cvt_f32_f16_e32 v98, v174
	s_mul_i32 s19, s11, 0x2200
	s_cmpk_eq_i32 s13, 0xfc0
	s_nop 0
	s_nop 0
	s_nop 2
	v_sub_f32_e32 v90, v98, v90
	v_cvt_f16_f32_e32 v90, v90
	s_nop 0
	s_nop 0
	s_nop 0
	ds_write_b16 v153, v90 offset:17408
	v_cvt_f32_f16_sdwa v90, v174 dst_sel:DWORD dst_unused:UNUSED_PAD src0_sel:WORD_1
	s_nop 0
	s_nop 0
	s_nop 0
	s_nop 0
	v_sub_f32_e32 v90, v90, v91
	v_cvt_f16_f32_e32 v90, v90
	s_nop 0
	ds_write_b16 v153, v90 offset:17552
	v_cvt_f32_f16_e32 v90, v175
	v_sub_f32_e32 v90, v90, v92
	v_cvt_f16_f32_e32 v90, v90
	ds_write_b16 v153, v90 offset:17696
	v_cvt_f32_f16_sdwa v90, v175 dst_sel:DWORD dst_unused:UNUSED_PAD src0_sel:WORD_1
	v_sub_f32_e32 v90, v90, v93
	v_cvt_f16_f32_e32 v90, v90
	ds_write_b16 v153, v90 offset:17840
	s_waitcnt lgkmcnt(0)
	s_barrier
; #define LAS __attribute__((address_space(3)))
; __device__ __forceinline__ f32x4 mma16(const h16x8 a, const h16x8 b, const f32x4 c) { return __builtin_amdgcn_mfma_f32_16x16x32_f16(a, b, c, 0, 0, 0); }
; __device__ __forceinline__ void phase_gdn_scan(const int wid_s, CParams& p, LAS unsigned char* lds) {
;     ...
;             {
;                 f32x4 acc = {0.f, 0.f, 0.f, 0.f};
; #pragma unroll
;                 for (int ks = 0; ks < 4; ++ks) acc = mma16(qf[ks], *(const LAS h16x8*)(Sc + (16 * vt + lr) * 136 + 32 * ks + 8 * lq), acc);
; #pragma unroll
;                 for (int ks = 0; ks < 2; ++ks) acc = mma16(inf[ks], *(const LAS h16x8*)(Vnt + (16 * vt + lr) * 72 + 32 * ks + 8 * lq), acc);
; #pragma unroll
;                 for (int r = 0; r < 4; ++r) y[(size_t)(tc0 + 16 * wq + 4 * lq + r) * D + 512 + h * 128 + 32 * sl + 16 * vt + lr] = (h16)acc[r];
;             }
; #pragma unroll
;             for (int i = 0; i < 2; ++i) {
;                 f32x4 acc = st[i] * __expf(egl);
; #pragma unroll
;                 for (int ks = 0; ks < 2; ++ks) acc = mma16(*(const LAS h16x8*)(Vnt + (16 * vt + lr) * 72 + 32 * ks + 8 * lq), kf[i][ks], acc);
;                 st[i] = acc;
; #pragma unroll
;                 for (int r = 0; r < 4; ++r) Sn[(16 * vt + 4 * lq + r) * 136 + 16 * (2 * wq + i) + lr] = (h16)acc[r];
;             }
;             __syncthreads();
;             cur ^= 1;
; #pragma unroll
;             for (int ks = 0; ks < 4; ++ks) { wf[ks] = wfn[ks]; qf[ks] = qfn[ks]; }
; #pragma unroll
;             for (int ks = 0; ks < 2; ++ks) { inf[ks] = infn[ks]; kf[0][ks] = kfn[0][ks]; kf[1][ks] = kfn[1][ks]; }
;             uu = uun; egl = egln;
	ds_read_b128 v[90:93], v135
	s_waitcnt lgkmcnt(0)
	v_mfma_f32_16x16x32_f16 v[90:93], v[94:97], v[90:93], 0
	ds_read_b128 v[94:97], v135 offset:64
	s_waitcnt lgkmcnt(0)
	v_mfma_f32_16x16x32_f16 v[90:93], v[102:105], v[94:97], v[90:93]
	ds_read_b128 v[94:97], v135 offset:128
	s_nop 0
	s_nop 0
	s_nop 0
	s_waitcnt lgkmcnt(0)
	v_mfma_f32_16x16x32_f16 v[90:93], v[106:109], v[94:97], v[90:93]
	ds_read_b128 v[94:97], v135 offset:192
	v_add_u32_e32 v135, v115, v118
	s_nop 0
	s_waitcnt lgkmcnt(0)
	v_mfma_f32_16x16x32_f16 v[90:93], v[162:165], v[94:97], v[90:93]
	ds_read_b128 v[94:97], v135 offset:17408
	s_nop 0
	s_nop 0
	s_nop 0
	s_waitcnt lgkmcnt(0)
	v_mfma_f32_16x16x32_f16 v[86:89], v[86:89], v[94:97], v[90:93]
	s_nop 0
	s_nop 1
	ds_read_b128 v[90:93], v135 offset:17472
	s_nop 0
	s_waitcnt lgkmcnt(0)
	v_mfma_f32_16x16x32_f16 v[82:85], v[82:85], v[90:93], v[86:89]
	s_nop 2
	v_add_u32_e32 v86, s12, v155
	v_ashrrev_i32_e32 v87, 31, v86
	v_lshlrev_b64 v[88:89], 11, v[86:87]
	s_nop 1
	v_cvt_f16_f32_e32 v82, v82
	v_lshl_add_u64 v[88:89], v[138:139], 0, v[88:89]
	v_cvt_f16_f32_e32 v87, v83
	v_cvt_f16_f32_e32 v84, v84
	global_store_short v[88:89], v82, off
	v_add_u32_e32 v82, 1, v86
	v_ashrrev_i32_e32 v83, 31, v82
	v_lshlrev_b64 v[82:83], 11, v[82:83]
	v_lshl_add_u64 v[82:83], v[138:139], 0, v[82:83]
	global_store_short v[82:83], v87, off
	v_add_u32_e32 v82, 2, v86
	v_ashrrev_i32_e32 v83, 31, v82
	v_lshlrev_b64 v[82:83], 11, v[82:83]
	v_lshl_add_u64 v[82:83], v[138:139], 0, v[82:83]
	global_store_short v[82:83], v84, off
	v_cvt_f16_f32_e32 v84, v85
	v_add_u32_e32 v82, 3, v86
	v_ashrrev_i32_e32 v83, 31, v82
	v_lshlrev_b64 v[82:83], 11, v[82:83]
	v_lshl_add_u64 v[82:83], v[138:139], 0, v[82:83]
	global_store_short v[82:83], v84, off
	v_mul_f32_e32 v82, 0x3fb8aa3b, v137
	v_exp_f32_e32 v82, v82
	s_mov_b32 s12, s13
	s_nop 0
	v_pk_mul_f32 v[24:25], v[24:25], v[82:83] op_sel_hi:[1,0]
	v_pk_mul_f32 v[22:23], v[22:23], v[82:83] op_sel_hi:[1,0]
	v_pk_mul_f32 v[12:13], v[12:13], v[82:83] op_sel_hi:[1,0]
	v_pk_mul_f32 v[10:11], v[10:11], v[82:83] op_sel_hi:[1,0]
	v_mfma_f32_16x16x32_f16 v[22:25], v[94:97], v[78:81], v[22:25]
	v_add3_u32 v78, v148, s19, v149
	s_nop 0
	s_nop 0
	v_mfma_f32_16x16x32_f16 v[22:25], v[90:93], v[74:77], v[22:25]
	s_nop 0
	s_nop 0
	s_nop 0
	s_nop 0
	s_nop 0
	s_nop 2
	v_cvt_f16_f32_e32 v74, v22
	s_nop 0
	ds_write_b16 v78, v74
	v_cvt_f16_f32_e32 v74, v23
	ds_write_b16 v78, v74 offset:272
	v_cvt_f16_f32_e32 v74, v24
	ds_write_b16 v78, v74 offset:544
	v_cvt_f16_f32_e32 v74, v25
	ds_write_b16 v78, v74 offset:816
	ds_read_b128 v[74:77], v135 offset:17408
	s_waitcnt lgkmcnt(0)
	v_mfma_f32_16x16x32_f16 v[10:13], v[74:77], v[70:73], v[10:13]
	ds_read_b128 v[70:73], v135 offset:17472
	s_waitcnt lgkmcnt(0)
	v_mfma_f32_16x16x32_f16 v[10:13], v[70:73], v[66:69], v[10:13]
	s_nop 7
	v_cvt_f16_f32_e32 v66, v10
	ds_write_b16 v78, v66 offset:32
	v_cvt_f16_f32_e32 v66, v11
	ds_write_b16 v78, v66 offset:304
	v_cvt_f16_f32_e32 v66, v12
	ds_write_b16 v78, v66 offset:576
	v_cvt_f16_f32_e32 v66, v13
	ds_write_b16 v78, v66 offset:848
	s_waitcnt vmcnt(4)
	v_mov_b32_e32 v110, v62
	v_mov_b32_e32 v111, v63
	v_mov_b32_e32 v112, v64
	v_mov_b32_e32 v113, v65
	v_mov_b32_e32 v98, v54
	v_mov_b32_e32 v99, v55
	v_mov_b32_e32 v100, v56
	v_mov_b32_e32 v101, v57
	v_mov_b32_e32 v102, v46
	v_mov_b32_e32 v103, v47
	v_mov_b32_e32 v104, v48
	v_mov_b32_e32 v105, v49
	v_mov_b32_e32 v106, v42
	v_mov_b32_e32 v107, v43
	v_mov_b32_e32 v108, v44
	v_mov_b32_e32 v109, v45
	v_mov_b32_e32 v94, v50
	v_mov_b32_e32 v95, v51
	v_mov_b32_e32 v90, v58
	v_mov_b32_e32 v91, v59
	v_mov_b32_e32 v92, v60
	v_mov_b32_e32 v93, v61
	v_mov_b32_e32 v96, v52
	v_mov_b32_e32 v97, v53
	s_waitcnt lgkmcnt(0)
	s_barrier
	s_cbranch_scc0 .LBB0_1285
; #define LAS __attribute__((address_space(3)))
; __device__ __forceinline__ f32x4 mma16(const h16x8 a, const h16x8 b, const f32x4 c) { return __builtin_amdgcn_mfma_f32_16x16x32_f16(a, b, c, 0, 0, 0); }
; __device__ __forceinline__ void phase_gdn_scan(const int wid_s, CParams& p, LAS unsigned char* lds) {
;     ...
;             {
;                 f32x4 acc = {0.f, 0.f, 0.f, 0.f};
; #pragma unroll
;                 for (int ks = 0; ks < 4; ++ks) acc = mma16(*(const LAS h16x8*)(Sc + (16 * vt + lr) * 136 + 32 * ks + 8 * lq), wf[ks], acc);
; #pragma unroll
;                 for (int r = 0; r < 4; ++r) Vnt[(16 * vt + 4 * lq + r) * 72 + 16 * wq + lr] = (h16)((float)uu[r] - acc[r]);
;             }
;             __syncthreads();
;             {
;                 f32x4 acc = {0.f, 0.f, 0.f, 0.f};
; #pragma unroll
;                 for (int ks = 0; ks < 4; ++ks) acc = mma16(qf[ks], *(const LAS h16x8*)(Sc + (16 * vt + lr) * 136 + 32 * ks + 8 * lq), acc);
; #pragma unroll
;                 for (int ks = 0; ks < 2; ++ks) acc = mma16(inf[ks], *(const LAS h16x8*)(Vnt + (16 * vt + lr) * 72 + 32 * ks + 8 * lq), acc);
; #pragma unroll
;                 for (int r = 0; r < 4; ++r) y[(size_t)(tc0 + 16 * wq + 4 * lq + r) * D + 512 + h * 128 + 32 * sl + 16 * vt + lr] = (h16)acc[r];
;             }
; #pragma unroll
;             for (int i = 0; i < 2; ++i) {
;                 f32x4 acc = st[i] * __expf(egl);
; #pragma unroll
;                 for (int ks = 0; ks < 2; ++ks) acc = mma16(*(const LAS h16x8*)(Vnt + (16 * vt + lr) * 72 + 32 * ks + 8 * lq), kf[i][ks], acc);
;                 st[i] = acc;
; #pragma unroll
;                 for (int r = 0; r < 4; ++r) Sn[(16 * vt + 4 * lq + r) * 136 + 16 * (2 * wq + i) + lr] = (h16)acc[r];
;             }
;             __syncthreads();
	ds_read_b128 v[66:69], v117 offset:8704
	v_add_u32_e32 v70, s10, v119
	v_readlane_b32 s6, v253, 0
	s_add_i32 s18, s18, s6
	v_readlane_b32 s6, v253, 57
	s_add_i32 s17, s17, s6
	s_cmpk_gt_i32 s18, 0xff
	s_waitcnt lgkmcnt(0)
	v_mfma_f32_16x16x32_f16 v[62:65], v[66:69], v[62:65], 0
	ds_read_b128 v[66:69], v117 offset:8768
	s_waitcnt lgkmcnt(0)
	v_mfma_f32_16x16x32_f16 v[58:61], v[66:69], v[58:61], v[62:65]
	s_nop 4
	ds_read_b128 v[62:65], v117 offset:8832
	s_waitcnt lgkmcnt(0)
	v_mfma_f32_16x16x32_f16 v[54:57], v[62:65], v[54:57], v[58:61]
	s_nop 2
	ds_read_b128 v[58:61], v117 offset:8896
	s_waitcnt lgkmcnt(0)
	v_mfma_f32_16x16x32_f16 v[38:41], v[58:61], v[38:41], v[54:57]
	s_nop 2
	v_cvt_f32_f16_e32 v54, v140
	s_nop 3
	v_sub_f32_e32 v38, v54, v38
	v_cvt_f16_f32_e32 v38, v38
	ds_write_b16 v153, v38 offset:17408
	v_cvt_f32_f16_sdwa v38, v140 dst_sel:DWORD dst_unused:UNUSED_PAD src0_sel:WORD_1
	v_sub_f32_e32 v38, v38, v39
	v_cvt_f16_f32_e32 v38, v38
	ds_write_b16 v153, v38 offset:17552
	v_cvt_f32_f16_e32 v38, v141
	v_sub_f32_e32 v38, v38, v40
	v_cvt_f16_f32_e32 v38, v38
	ds_write_b16 v153, v38 offset:17696
	v_cvt_f32_f16_sdwa v38, v141 dst_sel:DWORD dst_unused:UNUSED_PAD src0_sel:WORD_1
	v_sub_f32_e32 v38, v38, v41
	v_cvt_f16_f32_e32 v38, v38
	ds_write_b16 v153, v38 offset:17840
	s_waitcnt lgkmcnt(0)
	s_barrier
	ds_read_b128 v[38:41], v117 offset:8704
	s_waitcnt lgkmcnt(0)
	v_mfma_f32_16x16x32_f16 v[38:41], v[50:53], v[38:41], 0
	ds_read_b128 v[50:53], v117 offset:8768
	s_waitcnt lgkmcnt(0)
	v_mfma_f32_16x16x32_f16 v[38:41], v[46:49], v[50:53], v[38:41]
	ds_read_b128 v[46:49], v117 offset:8832
	s_waitcnt lgkmcnt(0)
	v_mfma_f32_16x16x32_f16 v[38:41], v[42:45], v[46:49], v[38:41]
	ds_read_b128 v[42:45], v117 offset:8896
	s_waitcnt vmcnt(11) lgkmcnt(0)
	v_mfma_f32_16x16x32_f16 v[30:33], v[30:33], v[42:45], v[38:41]
	s_nop 4
	ds_read_b128 v[38:41], v135 offset:17408
	s_waitcnt vmcnt(10) lgkmcnt(0)
	v_mfma_f32_16x16x32_f16 v[34:37], v[34:37], v[38:41], v[30:33]
	s_nop 2
	ds_read_b128 v[30:33], v135 offset:17472
	s_waitcnt vmcnt(9) lgkmcnt(0)
	v_mfma_f32_16x16x32_f16 v[26:29], v[26:29], v[30:33], v[34:37]
	s_nop 2
	v_add_u32_e32 v34, 0xfc0, v70
	v_ashrrev_i32_e32 v35, 31, v34
	s_nop 2
	v_cvt_f16_f32_e32 v26, v26
	v_lshlrev_b64 v[34:35], 11, v[34:35]
	v_lshl_add_u64 v[34:35], v[138:139], 0, v[34:35]
	v_cvt_f16_f32_e32 v28, v28
	global_store_short v[34:35], v26, off
	v_cvt_f16_f32_e32 v34, v27
	v_add_u32_e32 v26, 0xfc1, v70
	v_ashrrev_i32_e32 v27, 31, v26
	v_lshlrev_b64 v[26:27], 11, v[26:27]
	v_lshl_add_u64 v[26:27], v[138:139], 0, v[26:27]
	global_store_short v[26:27], v34, off
	v_add_u32_e32 v26, 0xfc2, v70
	v_ashrrev_i32_e32 v27, 31, v26
	v_lshlrev_b64 v[26:27], 11, v[26:27]
	v_lshl_add_u64 v[26:27], v[138:139], 0, v[26:27]
	global_store_short v[26:27], v28, off
	v_cvt_f16_f32_e32 v28, v29
	v_add_u32_e32 v26, 0xfc3, v70
	v_ashrrev_i32_e32 v27, 31, v26
	v_lshlrev_b64 v[26:27], 11, v[26:27]
	v_lshl_add_u64 v[26:27], v[138:139], 0, v[26:27]
	global_store_short v[26:27], v28, off
	s_waitcnt vmcnt(8)
	v_mul_f32_e32 v26, 0x3fb8aa3b, v154
	v_exp_f32_e32 v26, v26
	s_nop 0
	v_pk_mul_f32 v[24:25], v[26:27], v[24:25] op_sel_hi:[0,1]
	v_pk_mul_f32 v[22:23], v[26:27], v[22:23] op_sel_hi:[0,1]
	v_pk_mul_f32 v[12:13], v[26:27], v[12:13] op_sel_hi:[0,1]
	v_pk_mul_f32 v[10:11], v[26:27], v[10:11] op_sel_hi:[0,1]
	v_mfma_f32_16x16x32_f16 v[18:21], v[38:41], v[18:21], v[22:25]
	v_mfma_f32_16x16x32_f16 v[14:17], v[30:33], v[14:17], v[18:21]
	s_nop 6
	v_add_u32_e32 v18, v148, v149
	v_cvt_f16_f32_e32 v14, v14
	ds_write_b16 v18, v14
	v_cvt_f16_f32_e32 v14, v15
	ds_write_b16 v18, v14 offset:272
	v_cvt_f16_f32_e32 v14, v16
	ds_write_b16 v18, v14 offset:544
	v_cvt_f16_f32_e32 v14, v17
	ds_write_b16 v18, v14 offset:816
	ds_read_b128 v[14:17], v135 offset:17408
	s_waitcnt lgkmcnt(0)
	v_mfma_f32_16x16x32_f16 v[6:9], v[14:17], v[6:9], v[10:13]
	s_nop 2
	ds_read_b128 v[10:13], v135 offset:17472
	s_waitcnt lgkmcnt(0)
	v_mfma_f32_16x16x32_f16 v[2:5], v[10:13], v[2:5], v[6:9]
	s_nop 7
	v_cvt_f16_f32_e32 v2, v2
	ds_write_b16 v18, v2 offset:32
	v_cvt_f16_f32_e32 v2, v3
	ds_write_b16 v18, v2 offset:304
	v_cvt_f16_f32_e32 v2, v4
	ds_write_b16 v18, v2 offset:576
	v_cvt_f16_f32_e32 v2, v5
	ds_write_b16 v18, v2 offset:848
	s_waitcnt lgkmcnt(0)
	s_barrier
	s_cbranch_scc0 .LBB0_1281
